# G3 start de-phasing lengthened to 0/8/16/24 us
# speedup vs baseline: 1.0053x; 1.0030x over previous
.LBB0_366:
	s_cmp_lt_i32 s56, 5
	s_cselect_b64 s[0:1], -1, 0
	s_and_b64 s[8:9], s[0:1], s[4:5]
	s_andn2_b64 vcc, exec, s[8:9]
	s_cbranch_vccnz .LBB0_408
	s_bfe_u32 s0, s2, 0x20003
	s_cmp_eq_u32 s0, 0
	v_mbcnt_lo_u32_b32 v0, -1, 0
	v_mbcnt_hi_u32_b32 v0, -1, v0
	s_cbranch_scc1 .LBB0_370
	s_mul_i32 s0, s0, 4
